# v15 (w_gate/w_up conversion batches both in flight) + w_out conversion items in the in-projection tail: element loads batched (two batches of 8 in flight) instead of one element per full memory wait
# speedup vs baseline: 1.0095x; 1.0095x over previous
; #define LAS __attribute__((address_space(3)))
; template <class KS>
; __device__ __forceinline__ void p0_transpose_item(const float* W, int K, int N, bf16* WT, int kb, int nb, int prow, LAS float* scr, int lane, const KS& ks) {
;     const int k0 = 64 * kb, n0 = 32 * nb;
; #pragma unroll 8
;     for (int i = 0; i < 32; ++i) { const int kk = 2 * i + (lane >> 5); scr[kk * 33 + (lane & 31)] = W[(size_t)(k0 + kk) * N + n0 + (lane & 31)] * ks(k0 + kk); }
; __device__ __forceinline__ void convert_items(KArgs A, unsigned char* ws, LAS unsigned char* lds, int it0, int it1, int gw, int NGW, int wave, int lane) {
;     ...
;         if (r < CI_G) { const int kb = r / 88, nb = r % 88; const float* g2 = A->in.g2;
;             p0_transpose_item(A->in.wu, DM, DFF, WGU, kb, nb, 256 * (nb >> 2) + 128 + 32 * (nb & 3), scr, lane, [g2](int k) { return g2[k]; }); continue; } r -= CI_G;
.LBB0_361:
	s_lshl_b32 s34, s20, 1
	s_lshl_b32 s35, s19, 1
	v_add_u32_e32 v66, s34, v6
	v_add_u32_e32 v68, s35, v29
	v_add_u32_e32 v70, s34, v36
	v_add_u32_e32 v72, s35, v31
	v_add_u32_e32 v74, s34, v38
	v_add_u32_e32 v76, s35, v33
	v_add_u32_e32 v78, s34, v40
	v_add_u32_e32 v80, s35, v37
	v_add_u32_e32 v82, s34, v42
	v_add_u32_e32 v84, s35, v39
	v_add_u32_e32 v86, s34, v44
	v_add_u32_e32 v88, s35, v41
	v_add_u32_e32 v90, s34, v46
	v_add_u32_e32 v92, s35, v43
	v_add_u32_e32 v94, s34, v48
	v_add_u32_e32 v96, s35, v45
	v_ashrrev_i32_e32 v69, 31, v68
	v_ashrrev_i32_e32 v67, 31, v66
	v_mad_i64_i32 v[98:99], s[36:37], v66, s28, v[34:35]
	v_ashrrev_i32_e32 v73, 31, v72
	v_ashrrev_i32_e32 v71, 31, v70
	v_ashrrev_i32_e32 v77, 31, v76
	v_ashrrev_i32_e32 v75, 31, v74
	v_ashrrev_i32_e32 v81, 31, v80
	v_ashrrev_i32_e32 v79, 31, v78
	v_mad_i64_i32 v[100:101], s[36:37], v68, s28, v[34:35]
	v_mad_i64_i32 v[102:103], s[36:37], v70, s28, v[34:35]
	v_mad_i64_i32 v[104:105], s[36:37], v72, s28, v[34:35]
	v_mad_i64_i32 v[106:107], s[36:37], v74, s28, v[34:35]
	v_mad_i64_i32 v[108:109], s[36:37], v76, s28, v[34:35]
	v_mad_i64_i32 v[110:111], s[36:37], v78, s28, v[34:35]
	v_mad_i64_i32 v[112:113], s[36:37], v80, s28, v[34:35]
	v_ashrrev_i32_e32 v85, 31, v84
	v_ashrrev_i32_e32 v83, 31, v82
	v_mad_i64_i32 v[114:115], s[36:37], v82, s28, v[34:35]
	v_ashrrev_i32_e32 v89, 31, v88
	v_ashrrev_i32_e32 v87, 31, v86
	v_mad_i64_i32 v[118:119], s[36:37], v86, s28, v[34:35]
	v_ashrrev_i32_e32 v93, 31, v92
	v_ashrrev_i32_e32 v91, 31, v90
	v_mad_i64_i32 v[122:123], s[36:37], v90, s28, v[34:35]
	v_ashrrev_i32_e32 v97, 31, v96
	v_ashrrev_i32_e32 v95, 31, v94
	v_mad_i64_i32 v[126:127], s[36:37], v94, s28, v[34:35]
	global_load_dword v98, v[98:99], off
	s_nop 0
	global_load_dword v99, v[100:101], off
	v_lshl_add_u64 v[66:67], v[66:67], 2, s[8:9]
	v_lshl_add_u64 v[68:69], v[68:69], 2, s[8:9]
	v_lshl_add_u64 v[70:71], v[70:71], 2, s[8:9]
	v_lshl_add_u64 v[72:73], v[72:73], 2, s[8:9]
	v_lshl_add_u64 v[74:75], v[74:75], 2, s[8:9]
	v_lshl_add_u64 v[76:77], v[76:77], 2, s[8:9]
	v_lshl_add_u64 v[78:79], v[78:79], 2, s[8:9]
	v_lshl_add_u64 v[80:81], v[80:81], 2, s[8:9]
	v_mad_i64_i32 v[116:117], s[36:37], v84, s28, v[34:35]
	v_mad_i64_i32 v[120:121], s[36:37], v88, s28, v[34:35]
	v_mad_i64_i32 v[124:125], s[36:37], v92, s28, v[34:35]
	v_mad_i64_i32 v[128:129], s[36:37], v96, s28, v[34:35]
	global_load_dword v100, v[102:103], off
	global_load_dword v101, v[104:105], off
	s_nop 0
	global_load_dword v102, v[106:107], off
	global_load_dword v103, v[108:109], off
	global_load_dword v104, v[110:111], off
	global_load_dword v105, v[112:113], off
	s_nop 0
	global_load_dword v106, v[114:115], off
	global_load_dword v107, v[116:117], off
	v_lshl_add_u64 v[82:83], v[82:83], 2, s[8:9]
	v_lshl_add_u64 v[84:85], v[84:85], 2, s[8:9]
	global_load_dword v108, v[118:119], off
	global_load_dword v109, v[120:121], off
	v_lshl_add_u64 v[86:87], v[86:87], 2, s[8:9]
	v_lshl_add_u64 v[88:89], v[88:89], 2, s[8:9]
	global_load_dword v110, v[122:123], off
	global_load_dword v111, v[124:125], off
	v_lshl_add_u64 v[90:91], v[90:91], 2, s[8:9]
	v_lshl_add_u64 v[92:93], v[92:93], 2, s[8:9]
	global_load_dword v112, v[126:127], off
	global_load_dword v113, v[128:129], off
	v_lshl_add_u64 v[94:95], v[94:95], 2, s[8:9]
	v_lshl_add_u64 v[96:97], v[96:97], 2, s[8:9]
	global_load_dword v66, v[66:67], off
	s_nop 0
	global_load_dword v67, v[68:69], off
	s_nop 0
	global_load_dword v68, v[70:71], off
	global_load_dword v69, v[72:73], off
	s_nop 0
	global_load_dword v70, v[74:75], off
	global_load_dword v71, v[76:77], off
	global_load_dword v72, v[78:79], off
	global_load_dword v73, v[80:81], off
	s_nop 0
	global_load_dword v74, v[82:83], off
	global_load_dword v75, v[84:85], off
	global_load_dword v76, v[86:87], off
	global_load_dword v77, v[88:89], off
	global_load_dword v78, v[90:91], off
	global_load_dword v79, v[92:93], off
	global_load_dword v80, v[94:95], off
	global_load_dword v81, v[96:97], off
	s_add_i32 s20, s20, 16
	s_add_i32 s19, s19, 16
	s_add_i32 s21, s21, -16
	v_add_u32_e32 v49, s34, v2
	v_add_u32_e32 v47, s35, v1
	v_add_u32_e32 v65, s35, v3
	v_add_u32_e32 v86, s34, v20
	v_add_u32_e32 v92, s35, v5
	v_add_u32_e32 v90, s34, v22
	v_add_u32_e32 v96, s35, v11
	v_add_u32_e32 v94, s34, v24
	v_add_u32_e32 v116, s35, v21
	v_add_u32_e32 v114, s34, v26
	v_add_u32_e32 v120, s35, v23
	v_add_u32_e32 v118, s34, v28
	v_add_u32_e32 v124, s35, v25
	v_add_u32_e32 v122, s34, v30
	v_add_u32_e32 v128, s35, v27
	v_add_u32_e32 v126, s34, v32
	s_cmp_lg_u32 s21, 0
	v_mad_u64_u32 v[82:83], s[34:35], v49, s3, v[10:11]
	v_mad_u64_u32 v[84:85], s[34:35], v47, s3, v[10:11]
	v_mad_u64_u32 v[86:87], s[34:35], v86, s3, v[10:11]
	v_mad_u64_u32 v[88:89], s[34:35], v65, s3, v[10:11]
	v_mad_u64_u32 v[90:91], s[34:35], v90, s3, v[10:11]
	v_mad_u64_u32 v[92:93], s[34:35], v92, s3, v[10:11]
	v_mad_u64_u32 v[94:95], s[34:35], v94, s3, v[10:11]
	v_mad_u64_u32 v[96:97], s[34:35], v96, s3, v[10:11]
	v_mad_u64_u32 v[114:115], s[34:35], v114, s3, v[10:11]
	v_mad_u64_u32 v[116:117], s[34:35], v116, s3, v[10:11]
	v_mad_u64_u32 v[118:119], s[34:35], v118, s3, v[10:11]
	v_mad_u64_u32 v[120:121], s[34:35], v120, s3, v[10:11]
	v_mad_u64_u32 v[122:123], s[34:35], v122, s3, v[10:11]
	v_mad_u64_u32 v[124:125], s[34:35], v124, s3, v[10:11]
	v_mad_u64_u32 v[126:127], s[34:35], v126, s3, v[10:11]
	v_mad_u64_u32 v[128:129], s[34:35], v128, s3, v[10:11]
	s_lshl_b32 s34, s20, 1
	s_lshl_b32 s35, s19, 1
	v_add_u32_e32 v134, s34, v6
	v_add_u32_e32 v136, s35, v29
	v_add_u32_e32 v138, s34, v36
	v_add_u32_e32 v140, s35, v31
	v_add_u32_e32 v142, s34, v38
	v_add_u32_e32 v144, s35, v33
; template <class KS>
; __device__ __forceinline__ void p0_transpose_item(const float* W, int K, int N, bf16* WT, int kb, int nb, int prow, LAS float* scr, int lane, const KS& ks) {
;     ...
; #pragma unroll 8
;     for (int i = 0; i < 32; ++i) { const int kk = 2 * i + (lane >> 5); scr[kk * 33 + (lane & 31)] = W[(size_t)(k0 + kk) * N + n0 + (lane & 31)] * ks(k0 + kk); }
	v_add_u32_e32 v146, s34, v40
	v_add_u32_e32 v148, s35, v37
	v_add_u32_e32 v150, s34, v42
	v_add_u32_e32 v152, s35, v39
	v_add_u32_e32 v154, s34, v44
	v_add_u32_e32 v156, s35, v41
	v_add_u32_e32 v158, s34, v46
	v_add_u32_e32 v160, s35, v43
	v_add_u32_e32 v192, s34, v48
	v_add_u32_e32 v194, s35, v45
	v_ashrrev_i32_e32 v137, 31, v136
	v_ashrrev_i32_e32 v135, 31, v134
	v_mad_i64_i32 v[196:197], s[36:37], v134, s28, v[34:35]
	v_ashrrev_i32_e32 v141, 31, v140
	v_ashrrev_i32_e32 v139, 31, v138
	v_ashrrev_i32_e32 v145, 31, v144
	v_ashrrev_i32_e32 v143, 31, v142
	v_ashrrev_i32_e32 v149, 31, v148
	v_ashrrev_i32_e32 v147, 31, v146
	v_mad_i64_i32 v[198:199], s[36:37], v136, s28, v[34:35]
	v_mad_i64_i32 v[200:201], s[36:37], v138, s28, v[34:35]
	v_mad_i64_i32 v[202:203], s[36:37], v140, s28, v[34:35]
	v_mad_i64_i32 v[204:205], s[36:37], v142, s28, v[34:35]
	v_mad_i64_i32 v[206:207], s[36:37], v144, s28, v[34:35]
	v_mad_i64_i32 v[208:209], s[36:37], v146, s28, v[34:35]
	v_mad_i64_i32 v[210:211], s[36:37], v148, s28, v[34:35]
	v_ashrrev_i32_e32 v153, 31, v152
	v_ashrrev_i32_e32 v151, 31, v150
	v_mad_i64_i32 v[212:213], s[36:37], v150, s28, v[34:35]
	v_ashrrev_i32_e32 v157, 31, v156
	v_ashrrev_i32_e32 v155, 31, v154
	v_mad_i64_i32 v[216:217], s[36:37], v154, s28, v[34:35]
	v_ashrrev_i32_e32 v161, 31, v160
	v_ashrrev_i32_e32 v159, 31, v158
	v_mad_i64_i32 v[220:221], s[36:37], v158, s28, v[34:35]
	v_ashrrev_i32_e32 v195, 31, v194
	v_ashrrev_i32_e32 v193, 31, v192
	v_mad_i64_i32 v[224:225], s[36:37], v192, s28, v[34:35]
	global_load_dword v196, v[196:197], off
	s_nop 0
	global_load_dword v197, v[198:199], off
	v_lshl_add_u64 v[134:135], v[134:135], 2, s[8:9]
	v_lshl_add_u64 v[136:137], v[136:137], 2, s[8:9]
	v_lshl_add_u64 v[138:139], v[138:139], 2, s[8:9]
	v_lshl_add_u64 v[140:141], v[140:141], 2, s[8:9]
	v_lshl_add_u64 v[142:143], v[142:143], 2, s[8:9]
	v_lshl_add_u64 v[144:145], v[144:145], 2, s[8:9]
	v_lshl_add_u64 v[146:147], v[146:147], 2, s[8:9]
	v_lshl_add_u64 v[148:149], v[148:149], 2, s[8:9]
	v_mad_i64_i32 v[214:215], s[36:37], v152, s28, v[34:35]
	v_mad_i64_i32 v[218:219], s[36:37], v156, s28, v[34:35]
	v_mad_i64_i32 v[222:223], s[36:37], v160, s28, v[34:35]
	v_mad_i64_i32 v[226:227], s[36:37], v194, s28, v[34:35]
	global_load_dword v198, v[200:201], off
	global_load_dword v199, v[202:203], off
	s_nop 0
	global_load_dword v200, v[204:205], off
	global_load_dword v201, v[206:207], off
	global_load_dword v202, v[208:209], off
	global_load_dword v203, v[210:211], off
	s_nop 0
	global_load_dword v204, v[212:213], off
	global_load_dword v205, v[214:215], off
	v_lshl_add_u64 v[150:151], v[150:151], 2, s[8:9]
	v_lshl_add_u64 v[152:153], v[152:153], 2, s[8:9]
	global_load_dword v206, v[216:217], off
	global_load_dword v207, v[218:219], off
	v_lshl_add_u64 v[154:155], v[154:155], 2, s[8:9]
	v_lshl_add_u64 v[156:157], v[156:157], 2, s[8:9]
	global_load_dword v208, v[220:221], off
	global_load_dword v209, v[222:223], off
	v_lshl_add_u64 v[158:159], v[158:159], 2, s[8:9]
	v_lshl_add_u64 v[160:161], v[160:161], 2, s[8:9]
	global_load_dword v210, v[224:225], off
	global_load_dword v211, v[226:227], off
	v_lshl_add_u64 v[192:193], v[192:193], 2, s[8:9]
	v_lshl_add_u64 v[194:195], v[194:195], 2, s[8:9]
	global_load_dword v134, v[134:135], off
	s_nop 0
	global_load_dword v135, v[136:137], off
	s_nop 0
	global_load_dword v136, v[138:139], off
	global_load_dword v137, v[140:141], off
	s_nop 0
	global_load_dword v138, v[142:143], off
	global_load_dword v139, v[144:145], off
	global_load_dword v140, v[146:147], off
	global_load_dword v141, v[148:149], off
	s_nop 0
	global_load_dword v142, v[150:151], off
	global_load_dword v143, v[152:153], off
	global_load_dword v144, v[154:155], off
	global_load_dword v145, v[156:157], off
	global_load_dword v146, v[158:159], off
	global_load_dword v147, v[160:161], off
	global_load_dword v148, v[192:193], off
	global_load_dword v149, v[194:195], off
	s_add_i32 s20, s20, 16
	s_add_i32 s19, s19, 16
	s_add_i32 s21, s21, -16
	v_add_u32_e32 v229, s34, v2
	v_add_u32_e32 v228, s35, v1
	v_add_u32_e32 v232, s35, v3
	v_add_u32_e32 v154, s34, v20
	v_add_u32_e32 v160, s35, v5
	v_add_u32_e32 v158, s34, v22
	v_add_u32_e32 v194, s35, v11
	v_add_u32_e32 v192, s34, v24
	v_add_u32_e32 v214, s35, v21
	v_add_u32_e32 v212, s34, v26
	v_add_u32_e32 v218, s35, v23
	v_add_u32_e32 v216, s34, v28
	v_add_u32_e32 v222, s35, v25
	v_add_u32_e32 v220, s34, v30
	v_add_u32_e32 v226, s35, v27
	v_add_u32_e32 v224, s34, v32
	s_cmp_lg_u32 s21, 0
	v_mad_u64_u32 v[150:151], s[34:35], v229, s3, v[10:11]
	v_mad_u64_u32 v[152:153], s[34:35], v228, s3, v[10:11]
	v_mad_u64_u32 v[154:155], s[34:35], v154, s3, v[10:11]
	v_mad_u64_u32 v[156:157], s[34:35], v232, s3, v[10:11]
	v_mad_u64_u32 v[158:159], s[34:35], v158, s3, v[10:11]
	v_mad_u64_u32 v[160:161], s[34:35], v160, s3, v[10:11]
	v_mad_u64_u32 v[192:193], s[34:35], v192, s3, v[10:11]
	v_mad_u64_u32 v[194:195], s[34:35], v194, s3, v[10:11]
	v_mad_u64_u32 v[212:213], s[34:35], v212, s3, v[10:11]
	v_mad_u64_u32 v[214:215], s[34:35], v214, s3, v[10:11]
	v_mad_u64_u32 v[216:217], s[34:35], v216, s3, v[10:11]
	v_mad_u64_u32 v[218:219], s[34:35], v218, s3, v[10:11]
	v_mad_u64_u32 v[220:221], s[34:35], v220, s3, v[10:11]
	v_mad_u64_u32 v[222:223], s[34:35], v222, s3, v[10:11]
	v_mad_u64_u32 v[224:225], s[34:35], v224, s3, v[10:11]
	v_mad_u64_u32 v[226:227], s[34:35], v226, s3, v[10:11]
	s_waitcnt vmcnt(32)
; #define GAS __attribute__((address_space(1)))
; #define LAS __attribute__((address_space(3)))
; #define LDS_WAIT() asm volatile("s_waitcnt lgkmcnt(0)" ::: "memory")
; __device__ __forceinline__ unsigned pk2(float lo, float hi) { return pg8::cvt_pk_bf16(lo, hi); }
; template <class KS>
; __device__ __forceinline__ void p0_transpose_item(const float* W, int K, int N, bf16* WT, int kb, int nb, int prow, LAS float* scr, int lane, const KS& ks) {
;     ...
; #pragma unroll 8
;     for (int i = 0; i < 32; ++i) { const int kk = 2 * i + (lane >> 5); scr[kk * 33 + (lane & 31)] = W[(size_t)(k0 + kk) * N + n0 + (lane & 31)] * ks(k0 + kk); }
;     LDS_WAIT(); asm volatile("" ::: "memory");
;     const int c = lane & 7;
; #pragma unroll
;     for (int j = 0; j < 4; ++j) { const int n = (lane >> 3) + 8 * j; const LAS float* s = scr + (8 * c) * 33 + n;
;         v4u o; o.x = pk2(s[0 * 33], s[1 * 33]); o.y = pk2(s[2 * 33], s[3 * 33]); o.z = pk2(s[4 * 33], s[5 * 33]); o.w = pk2(s[6 * 33], s[7 * 33]);
;         *(GAS v4u*)(WT + (size_t)(prow + n) * K + k0 + 8 * c) = o; }
	v_pk_mul_f32 v[66:67], v[98:99], v[66:67]
	v_pk_mul_f32 v[68:69], v[100:101], v[68:69]
	v_pk_mul_f32 v[70:71], v[102:103], v[70:71]
	v_pk_mul_f32 v[72:73], v[104:105], v[72:73]
	v_pk_mul_f32 v[74:75], v[106:107], v[74:75]
	v_pk_mul_f32 v[76:77], v[108:109], v[76:77]
	v_pk_mul_f32 v[78:79], v[110:111], v[78:79]
	v_pk_mul_f32 v[80:81], v[112:113], v[80:81]
	ds_write_b32 v82, v66
	ds_write_b32 v84, v67
	ds_write_b32 v86, v68
	ds_write_b32 v88, v69
	ds_write_b32 v90, v70
	ds_write_b32 v92, v71
	ds_write_b32 v94, v72
	ds_write_b32 v96, v73
	ds_write_b32 v114, v74
	ds_write_b32 v116, v75
	ds_write_b32 v118, v76
	ds_write_b32 v120, v77
	ds_write_b32 v122, v78
	ds_write_b32 v124, v79
	ds_write_b32 v126, v80
	ds_write_b32 v128, v81
	s_waitcnt vmcnt(0)
	v_pk_mul_f32 v[134:135], v[196:197], v[134:135]
	v_pk_mul_f32 v[136:137], v[198:199], v[136:137]
	v_pk_mul_f32 v[138:139], v[200:201], v[138:139]
	v_pk_mul_f32 v[140:141], v[202:203], v[140:141]
	v_pk_mul_f32 v[142:143], v[204:205], v[142:143]
	v_pk_mul_f32 v[144:145], v[206:207], v[144:145]
	v_pk_mul_f32 v[146:147], v[208:209], v[146:147]
	v_pk_mul_f32 v[148:149], v[210:211], v[148:149]
	ds_write_b32 v150, v134
	ds_write_b32 v152, v135
	ds_write_b32 v154, v136
	ds_write_b32 v156, v137
	ds_write_b32 v158, v138
	ds_write_b32 v160, v139
	ds_write_b32 v192, v140
	ds_write_b32 v194, v141
	ds_write_b32 v212, v142
	ds_write_b32 v214, v143
	ds_write_b32 v216, v144
	ds_write_b32 v218, v145
	ds_write_b32 v220, v146
	ds_write_b32 v222, v147
	ds_write_b32 v224, v148
	ds_write_b32 v226, v149
	s_lshl_b32 s8, s12, 6
	s_waitcnt lgkmcnt(0)
	s_and_b32 s8, s8, 0x1f00
	s_and_b32 s9, s11, 0x60
	s_or_b32 s8, s8, s9
	ds_read2_b32 v[38:39], v51 offset0:33 offset1:41
	ds_read2_b32 v[40:41], v51 offset1:8
	ds_read2_b32 v[42:43], v51 offset0:66 offset1:74
	ds_read2_b32 v[44:45], v51 offset0:99 offset1:107
	ds_read2_b32 v[46:47], v51 offset0:132 offset1:140
	ds_read2_b32 v[48:49], v51 offset0:165 offset1:173
	ds_read2_b32 v[66:67], v51 offset0:198 offset1:206
	ds_read2_b32 v[68:69], v51 offset0:231 offset1:239
	s_bitset1_b32 s8, 7
	s_and_b32 s9, 0xffff, s10
	v_add_u32_e32 v72, s8, v50
	s_lshl_b32 s12, s9, 1
	v_ashrrev_i32_e32 v73, 31, v72
	v_lshl_add_u64 v[70:71], v[14:15], 0, s[12:13]
	v_lshlrev_b64 v[72:73], 11, v[72:73]
	s_waitcnt lgkmcnt(6)
	v_cvt_pk_bf16_f32 v34, v40, v38
	s_waitcnt lgkmcnt(4)
	v_cvt_pk_bf16_f32 v35, v42, v44
	s_waitcnt lgkmcnt(2)
	v_cvt_pk_bf16_f32 v36, v46, v48
	s_waitcnt lgkmcnt(0)
	v_cvt_pk_bf16_f32 v37, v66, v68
	v_lshl_add_u64 v[72:73], v[70:71], 0, v[72:73]
	v_add_u32_e32 v38, s8, v52
	global_store_dwordx4 v[72:73], v[34:37], off
	s_nop 1
	v_cvt_pk_bf16_f32 v34, v41, v39
	v_ashrrev_i32_e32 v39, 31, v38
	v_cvt_pk_bf16_f32 v35, v43, v45
	v_cvt_pk_bf16_f32 v36, v47, v49
	v_cvt_pk_bf16_f32 v37, v67, v69
	v_lshlrev_b64 v[38:39], 11, v[38:39]
	ds_read2_b32 v[40:41], v51 offset0:49 offset1:57
	ds_read2_b32 v[42:43], v51 offset0:16 offset1:24
	ds_read2_b32 v[44:45], v51 offset0:82 offset1:90
	ds_read2_b32 v[46:47], v51 offset0:115 offset1:123
	ds_read2_b32 v[48:49], v51 offset0:148 offset1:156
	ds_read2_b32 v[66:67], v51 offset0:181 offset1:189
	ds_read2_b32 v[68:69], v51 offset0:214 offset1:222
	ds_read2_b32 v[72:73], v51 offset0:247 offset1:255
	v_lshl_add_u64 v[38:39], v[70:71], 0, v[38:39]
	global_store_dwordx4 v[38:39], v[34:37], off
	v_add_u32_e32 v38, s8, v53
	v_ashrrev_i32_e32 v39, 31, v38
	v_lshlrev_b64 v[38:39], 11, v[38:39]
	s_waitcnt lgkmcnt(6)
	v_cvt_pk_bf16_f32 v34, v42, v40
	s_waitcnt lgkmcnt(4)
	v_cvt_pk_bf16_f32 v35, v44, v46
	s_waitcnt lgkmcnt(2)
	v_cvt_pk_bf16_f32 v36, v48, v66
	s_waitcnt lgkmcnt(0)
	v_cvt_pk_bf16_f32 v37, v68, v72
	v_lshl_add_u64 v[38:39], v[70:71], 0, v[38:39]
	global_store_dwordx4 v[38:39], v[34:37], off
	v_add_u32_e32 v38, s8, v54
	v_ashrrev_i32_e32 v39, 31, v38
	v_lshlrev_b64 v[38:39], 11, v[38:39]
	v_cvt_pk_bf16_f32 v34, v43, v41
	v_cvt_pk_bf16_f32 v35, v45, v47
	v_cvt_pk_bf16_f32 v36, v49, v67
	v_cvt_pk_bf16_f32 v37, v69, v73
	v_lshl_add_u64 v[38:39], v[70:71], 0, v[38:39]
	global_store_dwordx4 v[38:39], v[34:37], off
	s_waitcnt lgkmcnt(0)

; #define LAS __attribute__((address_space(3)))
; template <class KS>
; __device__ __forceinline__ void p0_transpose_item(const float* W, int K, int N, bf16* WT, int kb, int nb, int prow, LAS float* scr, int lane, const KS& ks) {
;     const int k0 = 64 * kb, n0 = 32 * nb;
; #pragma unroll 8
;     for (int i = 0; i < 32; ++i) { const int kk = 2 * i + (lane >> 5); scr[kk * 33 + (lane & 31)] = W[(size_t)(k0 + kk) * N + n0 + (lane & 31)] * ks(k0 + kk); }
; __device__ __forceinline__ void convert_items(KArgs A, unsigned char* ws, LAS unsigned char* lds, int it0, int it1, int gw, int NGW, int wave, int lane) {
;     ...
;         if (r < CI_G) { const int kb = r / 88, nb = r % 88; const float* g2 = A->in.g2;
;             p0_transpose_item(A->in.wg, DM, DFF, WGU, kb, nb, 256 * (nb >> 2) + 32 * (nb & 3), scr, lane, [g2](int k) { return g2[k]; }); continue; } r -= CI_G;
.LBB0_366:
	s_lshl_b32 s34, s11, 1
	s_lshl_b32 s35, s10, 1
	v_add_u32_e32 v66, s34, v6
	v_add_u32_e32 v68, s35, v29
	v_add_u32_e32 v70, s34, v36
	v_add_u32_e32 v72, s35, v31
	v_add_u32_e32 v74, s34, v38
	v_add_u32_e32 v76, s35, v33
	v_add_u32_e32 v78, s34, v40
	v_add_u32_e32 v80, s35, v37
	v_add_u32_e32 v82, s34, v42
	v_add_u32_e32 v84, s35, v39
	v_add_u32_e32 v86, s34, v44
	v_add_u32_e32 v88, s35, v41
	v_add_u32_e32 v90, s34, v46
	v_add_u32_e32 v92, s35, v43
	v_add_u32_e32 v94, s34, v48
	v_add_u32_e32 v96, s35, v45
	v_ashrrev_i32_e32 v69, 31, v68
	v_ashrrev_i32_e32 v67, 31, v66
	v_mad_i64_i32 v[98:99], s[36:37], v66, s28, v[34:35]
	v_ashrrev_i32_e32 v73, 31, v72
	v_ashrrev_i32_e32 v71, 31, v70
	v_ashrrev_i32_e32 v77, 31, v76
	v_ashrrev_i32_e32 v75, 31, v74
	v_ashrrev_i32_e32 v81, 31, v80
	v_ashrrev_i32_e32 v79, 31, v78
	v_mad_i64_i32 v[100:101], s[36:37], v68, s28, v[34:35]
	v_mad_i64_i32 v[102:103], s[36:37], v70, s28, v[34:35]
	v_mad_i64_i32 v[104:105], s[36:37], v72, s28, v[34:35]
	v_mad_i64_i32 v[106:107], s[36:37], v74, s28, v[34:35]
	v_mad_i64_i32 v[108:109], s[36:37], v76, s28, v[34:35]
	v_mad_i64_i32 v[110:111], s[36:37], v78, s28, v[34:35]
	v_mad_i64_i32 v[112:113], s[36:37], v80, s28, v[34:35]
	v_ashrrev_i32_e32 v85, 31, v84
	v_ashrrev_i32_e32 v83, 31, v82
	v_mad_i64_i32 v[114:115], s[36:37], v82, s28, v[34:35]
	v_ashrrev_i32_e32 v89, 31, v88
	v_ashrrev_i32_e32 v87, 31, v86
	v_mad_i64_i32 v[118:119], s[36:37], v86, s28, v[34:35]
	v_ashrrev_i32_e32 v93, 31, v92
	v_ashrrev_i32_e32 v91, 31, v90
	v_mad_i64_i32 v[122:123], s[36:37], v90, s28, v[34:35]
	v_ashrrev_i32_e32 v97, 31, v96
	v_ashrrev_i32_e32 v95, 31, v94
	v_mad_i64_i32 v[126:127], s[36:37], v94, s28, v[34:35]
	global_load_dword v98, v[98:99], off
	s_nop 0
	global_load_dword v99, v[100:101], off
	v_lshl_add_u64 v[66:67], v[66:67], 2, s[8:9]
	v_lshl_add_u64 v[68:69], v[68:69], 2, s[8:9]
	v_lshl_add_u64 v[70:71], v[70:71], 2, s[8:9]
	v_lshl_add_u64 v[72:73], v[72:73], 2, s[8:9]
	v_lshl_add_u64 v[74:75], v[74:75], 2, s[8:9]
	v_lshl_add_u64 v[76:77], v[76:77], 2, s[8:9]
	v_lshl_add_u64 v[78:79], v[78:79], 2, s[8:9]
	v_lshl_add_u64 v[80:81], v[80:81], 2, s[8:9]
	v_mad_i64_i32 v[116:117], s[36:37], v84, s28, v[34:35]
	v_mad_i64_i32 v[120:121], s[36:37], v88, s28, v[34:35]
	v_mad_i64_i32 v[124:125], s[36:37], v92, s28, v[34:35]
	v_mad_i64_i32 v[128:129], s[36:37], v96, s28, v[34:35]
	global_load_dword v100, v[102:103], off
	global_load_dword v101, v[104:105], off
	s_nop 0
	global_load_dword v102, v[106:107], off
	global_load_dword v103, v[108:109], off
	global_load_dword v104, v[110:111], off
	global_load_dword v105, v[112:113], off
	s_nop 0
	global_load_dword v106, v[114:115], off
	global_load_dword v107, v[116:117], off
	v_lshl_add_u64 v[82:83], v[82:83], 2, s[8:9]
	v_lshl_add_u64 v[84:85], v[84:85], 2, s[8:9]
	global_load_dword v108, v[118:119], off
	global_load_dword v109, v[120:121], off
	v_lshl_add_u64 v[86:87], v[86:87], 2, s[8:9]
	v_lshl_add_u64 v[88:89], v[88:89], 2, s[8:9]
	global_load_dword v110, v[122:123], off
	global_load_dword v111, v[124:125], off
	v_lshl_add_u64 v[90:91], v[90:91], 2, s[8:9]
	v_lshl_add_u64 v[92:93], v[92:93], 2, s[8:9]
	global_load_dword v112, v[126:127], off
	global_load_dword v113, v[128:129], off
	v_lshl_add_u64 v[94:95], v[94:95], 2, s[8:9]
	v_lshl_add_u64 v[96:97], v[96:97], 2, s[8:9]
	global_load_dword v66, v[66:67], off
	s_nop 0
	global_load_dword v67, v[68:69], off
	s_nop 0
	global_load_dword v68, v[70:71], off
	global_load_dword v69, v[72:73], off
	s_nop 0
	global_load_dword v70, v[74:75], off
	global_load_dword v71, v[76:77], off
	global_load_dword v72, v[78:79], off
	global_load_dword v73, v[80:81], off
	s_nop 0
	global_load_dword v74, v[82:83], off
	global_load_dword v75, v[84:85], off
	global_load_dword v76, v[86:87], off
	global_load_dword v77, v[88:89], off
	global_load_dword v78, v[90:91], off
	global_load_dword v79, v[92:93], off
	global_load_dword v80, v[94:95], off
	global_load_dword v81, v[96:97], off
	s_add_i32 s11, s11, 16
	s_add_i32 s10, s10, 16
	s_add_i32 s21, s21, -16
	v_add_u32_e32 v49, s34, v2
	v_add_u32_e32 v47, s35, v1
	v_add_u32_e32 v65, s35, v3
	v_add_u32_e32 v86, s34, v20
	v_add_u32_e32 v92, s35, v5
	v_add_u32_e32 v90, s34, v22
	v_add_u32_e32 v96, s35, v11
	v_add_u32_e32 v94, s34, v24
	v_add_u32_e32 v116, s35, v21
	v_add_u32_e32 v114, s34, v26
	v_add_u32_e32 v120, s35, v23
	v_add_u32_e32 v118, s34, v28
	v_add_u32_e32 v124, s35, v25
	v_add_u32_e32 v122, s34, v30
	v_add_u32_e32 v128, s35, v27
	v_add_u32_e32 v126, s34, v32
	s_cmp_lg_u32 s21, 0
	v_mad_u64_u32 v[82:83], s[34:35], v49, s3, v[10:11]
	v_mad_u64_u32 v[84:85], s[34:35], v47, s3, v[10:11]
	v_mad_u64_u32 v[86:87], s[34:35], v86, s3, v[10:11]
	v_mad_u64_u32 v[88:89], s[34:35], v65, s3, v[10:11]
	v_mad_u64_u32 v[90:91], s[34:35], v90, s3, v[10:11]
	v_mad_u64_u32 v[92:93], s[34:35], v92, s3, v[10:11]
	v_mad_u64_u32 v[94:95], s[34:35], v94, s3, v[10:11]
	v_mad_u64_u32 v[96:97], s[34:35], v96, s3, v[10:11]
	v_mad_u64_u32 v[114:115], s[34:35], v114, s3, v[10:11]
	v_mad_u64_u32 v[116:117], s[34:35], v116, s3, v[10:11]
	v_mad_u64_u32 v[118:119], s[34:35], v118, s3, v[10:11]
	v_mad_u64_u32 v[120:121], s[34:35], v120, s3, v[10:11]
	v_mad_u64_u32 v[122:123], s[34:35], v122, s3, v[10:11]
	v_mad_u64_u32 v[124:125], s[34:35], v124, s3, v[10:11]
	v_mad_u64_u32 v[126:127], s[34:35], v126, s3, v[10:11]
	v_mad_u64_u32 v[128:129], s[34:35], v128, s3, v[10:11]
	s_lshl_b32 s34, s11, 1
	s_lshl_b32 s35, s10, 1
	v_add_u32_e32 v134, s34, v6
	v_add_u32_e32 v136, s35, v29
	v_add_u32_e32 v138, s34, v36
	v_add_u32_e32 v140, s35, v31
	v_add_u32_e32 v142, s34, v38
	v_add_u32_e32 v144, s35, v33
; template <class KS>
; __device__ __forceinline__ void p0_transpose_item(const float* W, int K, int N, bf16* WT, int kb, int nb, int prow, LAS float* scr, int lane, const KS& ks) {
;     ...
; #pragma unroll 8
;     for (int i = 0; i < 32; ++i) { const int kk = 2 * i + (lane >> 5); scr[kk * 33 + (lane & 31)] = W[(size_t)(k0 + kk) * N + n0 + (lane & 31)] * ks(k0 + kk); }
	v_add_u32_e32 v146, s34, v40
	v_add_u32_e32 v148, s35, v37
	v_add_u32_e32 v150, s34, v42
	v_add_u32_e32 v152, s35, v39
	v_add_u32_e32 v154, s34, v44
	v_add_u32_e32 v156, s35, v41
	v_add_u32_e32 v158, s34, v46
	v_add_u32_e32 v160, s35, v43
	v_add_u32_e32 v192, s34, v48
	v_add_u32_e32 v194, s35, v45
	v_ashrrev_i32_e32 v137, 31, v136
	v_ashrrev_i32_e32 v135, 31, v134
	v_mad_i64_i32 v[196:197], s[36:37], v134, s28, v[34:35]
	v_ashrrev_i32_e32 v141, 31, v140
	v_ashrrev_i32_e32 v139, 31, v138
	v_ashrrev_i32_e32 v145, 31, v144
	v_ashrrev_i32_e32 v143, 31, v142
	v_ashrrev_i32_e32 v149, 31, v148
	v_ashrrev_i32_e32 v147, 31, v146
	v_mad_i64_i32 v[198:199], s[36:37], v136, s28, v[34:35]
	v_mad_i64_i32 v[200:201], s[36:37], v138, s28, v[34:35]
	v_mad_i64_i32 v[202:203], s[36:37], v140, s28, v[34:35]
	v_mad_i64_i32 v[204:205], s[36:37], v142, s28, v[34:35]
	v_mad_i64_i32 v[206:207], s[36:37], v144, s28, v[34:35]
	v_mad_i64_i32 v[208:209], s[36:37], v146, s28, v[34:35]
	v_mad_i64_i32 v[210:211], s[36:37], v148, s28, v[34:35]
	v_ashrrev_i32_e32 v153, 31, v152
	v_ashrrev_i32_e32 v151, 31, v150
	v_mad_i64_i32 v[212:213], s[36:37], v150, s28, v[34:35]
	v_ashrrev_i32_e32 v157, 31, v156
	v_ashrrev_i32_e32 v155, 31, v154
	v_mad_i64_i32 v[216:217], s[36:37], v154, s28, v[34:35]
	v_ashrrev_i32_e32 v161, 31, v160
	v_ashrrev_i32_e32 v159, 31, v158
	v_mad_i64_i32 v[220:221], s[36:37], v158, s28, v[34:35]
	v_ashrrev_i32_e32 v195, 31, v194
	v_ashrrev_i32_e32 v193, 31, v192
	v_mad_i64_i32 v[224:225], s[36:37], v192, s28, v[34:35]
	global_load_dword v196, v[196:197], off
	s_nop 0
	global_load_dword v197, v[198:199], off
	v_lshl_add_u64 v[134:135], v[134:135], 2, s[8:9]
	v_lshl_add_u64 v[136:137], v[136:137], 2, s[8:9]
	v_lshl_add_u64 v[138:139], v[138:139], 2, s[8:9]
	v_lshl_add_u64 v[140:141], v[140:141], 2, s[8:9]
	v_lshl_add_u64 v[142:143], v[142:143], 2, s[8:9]
	v_lshl_add_u64 v[144:145], v[144:145], 2, s[8:9]
	v_lshl_add_u64 v[146:147], v[146:147], 2, s[8:9]
	v_lshl_add_u64 v[148:149], v[148:149], 2, s[8:9]
	v_mad_i64_i32 v[214:215], s[36:37], v152, s28, v[34:35]
	v_mad_i64_i32 v[218:219], s[36:37], v156, s28, v[34:35]
	v_mad_i64_i32 v[222:223], s[36:37], v160, s28, v[34:35]
	v_mad_i64_i32 v[226:227], s[36:37], v194, s28, v[34:35]
	global_load_dword v198, v[200:201], off
	global_load_dword v199, v[202:203], off
	s_nop 0
	global_load_dword v200, v[204:205], off
	global_load_dword v201, v[206:207], off
	global_load_dword v202, v[208:209], off
	global_load_dword v203, v[210:211], off
	s_nop 0
	global_load_dword v204, v[212:213], off
	global_load_dword v205, v[214:215], off
	v_lshl_add_u64 v[150:151], v[150:151], 2, s[8:9]
	v_lshl_add_u64 v[152:153], v[152:153], 2, s[8:9]
	global_load_dword v206, v[216:217], off
	global_load_dword v207, v[218:219], off
	v_lshl_add_u64 v[154:155], v[154:155], 2, s[8:9]
	v_lshl_add_u64 v[156:157], v[156:157], 2, s[8:9]
	global_load_dword v208, v[220:221], off
	global_load_dword v209, v[222:223], off
	v_lshl_add_u64 v[158:159], v[158:159], 2, s[8:9]
	v_lshl_add_u64 v[160:161], v[160:161], 2, s[8:9]
	global_load_dword v210, v[224:225], off
	global_load_dword v211, v[226:227], off
	v_lshl_add_u64 v[192:193], v[192:193], 2, s[8:9]
	v_lshl_add_u64 v[194:195], v[194:195], 2, s[8:9]
	global_load_dword v134, v[134:135], off
	s_nop 0
	global_load_dword v135, v[136:137], off
	s_nop 0
	global_load_dword v136, v[138:139], off
	global_load_dword v137, v[140:141], off
	s_nop 0
	global_load_dword v138, v[142:143], off
	global_load_dword v139, v[144:145], off
	global_load_dword v140, v[146:147], off
	global_load_dword v141, v[148:149], off
	s_nop 0
	global_load_dword v142, v[150:151], off
	global_load_dword v143, v[152:153], off
	global_load_dword v144, v[154:155], off
	global_load_dword v145, v[156:157], off
	global_load_dword v146, v[158:159], off
	global_load_dword v147, v[160:161], off
	global_load_dword v148, v[192:193], off
	global_load_dword v149, v[194:195], off
	s_add_i32 s11, s11, 16
	s_add_i32 s10, s10, 16
	s_add_i32 s21, s21, -16
	v_add_u32_e32 v229, s34, v2
	v_add_u32_e32 v228, s35, v1
	v_add_u32_e32 v232, s35, v3
	v_add_u32_e32 v154, s34, v20
	v_add_u32_e32 v160, s35, v5
	v_add_u32_e32 v158, s34, v22
	v_add_u32_e32 v194, s35, v11
	v_add_u32_e32 v192, s34, v24
	v_add_u32_e32 v214, s35, v21
	v_add_u32_e32 v212, s34, v26
	v_add_u32_e32 v218, s35, v23
	v_add_u32_e32 v216, s34, v28
	v_add_u32_e32 v222, s35, v25
	v_add_u32_e32 v220, s34, v30
	v_add_u32_e32 v226, s35, v27
	v_add_u32_e32 v224, s34, v32
	s_cmp_lg_u32 s21, 0
	v_mad_u64_u32 v[150:151], s[34:35], v229, s3, v[10:11]
	v_mad_u64_u32 v[152:153], s[34:35], v228, s3, v[10:11]
	v_mad_u64_u32 v[154:155], s[34:35], v154, s3, v[10:11]
	v_mad_u64_u32 v[156:157], s[34:35], v232, s3, v[10:11]
	v_mad_u64_u32 v[158:159], s[34:35], v158, s3, v[10:11]
	v_mad_u64_u32 v[160:161], s[34:35], v160, s3, v[10:11]
	v_mad_u64_u32 v[192:193], s[34:35], v192, s3, v[10:11]
	v_mad_u64_u32 v[194:195], s[34:35], v194, s3, v[10:11]
	v_mad_u64_u32 v[212:213], s[34:35], v212, s3, v[10:11]
	v_mad_u64_u32 v[214:215], s[34:35], v214, s3, v[10:11]
	v_mad_u64_u32 v[216:217], s[34:35], v216, s3, v[10:11]
	v_mad_u64_u32 v[218:219], s[34:35], v218, s3, v[10:11]
	v_mad_u64_u32 v[220:221], s[34:35], v220, s3, v[10:11]
	v_mad_u64_u32 v[222:223], s[34:35], v222, s3, v[10:11]
	v_mad_u64_u32 v[224:225], s[34:35], v224, s3, v[10:11]
	v_mad_u64_u32 v[226:227], s[34:35], v226, s3, v[10:11]
	s_waitcnt vmcnt(32)
; #define GAS __attribute__((address_space(1)))
; #define LAS __attribute__((address_space(3)))
; #define LDS_WAIT() asm volatile("s_waitcnt lgkmcnt(0)" ::: "memory")
; __device__ __forceinline__ unsigned pk2(float lo, float hi) { return pg8::cvt_pk_bf16(lo, hi); }
; template <class KS>
; __device__ __forceinline__ void p0_transpose_item(const float* W, int K, int N, bf16* WT, int kb, int nb, int prow, LAS float* scr, int lane, const KS& ks) {
;     ...
; #pragma unroll 8
;     for (int i = 0; i < 32; ++i) { const int kk = 2 * i + (lane >> 5); scr[kk * 33 + (lane & 31)] = W[(size_t)(k0 + kk) * N + n0 + (lane & 31)] * ks(k0 + kk); }
;     LDS_WAIT(); asm volatile("" ::: "memory");
;     const int c = lane & 7;
; #pragma unroll
;     for (int j = 0; j < 4; ++j) { const int n = (lane >> 3) + 8 * j; const LAS float* s = scr + (8 * c) * 33 + n;
;         v4u o; o.x = pk2(s[0 * 33], s[1 * 33]); o.y = pk2(s[2 * 33], s[3 * 33]); o.z = pk2(s[4 * 33], s[5 * 33]); o.w = pk2(s[6 * 33], s[7 * 33]);
;         *(GAS v4u*)(WT + (size_t)(prow + n) * K + k0 + 8 * c) = o; }
	v_pk_mul_f32 v[66:67], v[98:99], v[66:67]
	v_pk_mul_f32 v[68:69], v[100:101], v[68:69]
	v_pk_mul_f32 v[70:71], v[102:103], v[70:71]
	v_pk_mul_f32 v[72:73], v[104:105], v[72:73]
	v_pk_mul_f32 v[74:75], v[106:107], v[74:75]
	v_pk_mul_f32 v[76:77], v[108:109], v[76:77]
	v_pk_mul_f32 v[78:79], v[110:111], v[78:79]
	v_pk_mul_f32 v[80:81], v[112:113], v[80:81]
	ds_write_b32 v82, v66
	ds_write_b32 v84, v67
	ds_write_b32 v86, v68
	ds_write_b32 v88, v69
	ds_write_b32 v90, v70
	ds_write_b32 v92, v71
	ds_write_b32 v94, v72
	ds_write_b32 v96, v73
	ds_write_b32 v114, v74
	ds_write_b32 v116, v75
	ds_write_b32 v118, v76
	ds_write_b32 v120, v77
	ds_write_b32 v122, v78
	ds_write_b32 v124, v79
	ds_write_b32 v126, v80
	ds_write_b32 v128, v81
	s_waitcnt vmcnt(0)
	v_pk_mul_f32 v[134:135], v[196:197], v[134:135]
	v_pk_mul_f32 v[136:137], v[198:199], v[136:137]
	v_pk_mul_f32 v[138:139], v[200:201], v[138:139]
	v_pk_mul_f32 v[140:141], v[202:203], v[140:141]
	v_pk_mul_f32 v[142:143], v[204:205], v[142:143]
	v_pk_mul_f32 v[144:145], v[206:207], v[144:145]
	v_pk_mul_f32 v[146:147], v[208:209], v[146:147]
	v_pk_mul_f32 v[148:149], v[210:211], v[148:149]
	ds_write_b32 v150, v134
	ds_write_b32 v152, v135
	ds_write_b32 v154, v136
	ds_write_b32 v156, v137
	ds_write_b32 v158, v138
	ds_write_b32 v160, v139
	ds_write_b32 v192, v140
	ds_write_b32 v194, v141
	ds_write_b32 v212, v142
	ds_write_b32 v214, v143
	ds_write_b32 v216, v144
	ds_write_b32 v218, v145
	ds_write_b32 v220, v146
	ds_write_b32 v222, v147
	ds_write_b32 v224, v148
	ds_write_b32 v226, v149
	s_waitcnt lgkmcnt(0)
	s_lshl_b32 s8, s19, 6
	s_and_b32 s9, s20, 0x60
	s_and_b32 s8, s8, 0x1f00
	ds_read2_b32 v[38:39], v51 offset0:33 offset1:41
	ds_read2_b32 v[40:41], v51 offset1:8
	ds_read2_b32 v[42:43], v51 offset0:66 offset1:74
	ds_read2_b32 v[44:45], v51 offset0:99 offset1:107
	ds_read2_b32 v[46:47], v51 offset0:132 offset1:140
	ds_read2_b32 v[48:49], v51 offset0:165 offset1:173
	ds_read2_b32 v[66:67], v51 offset0:198 offset1:206
	ds_read2_b32 v[68:69], v51 offset0:231 offset1:239
	s_or_b32 s8, s8, s9
	s_and_b32 s9, 0xffff, s12
	v_add_u32_e32 v72, s8, v50
	s_lshl_b32 s12, s9, 1
	v_ashrrev_i32_e32 v73, 31, v72
	v_lshl_add_u64 v[70:71], v[14:15], 0, s[12:13]
	v_lshlrev_b64 v[72:73], 11, v[72:73]
	s_waitcnt lgkmcnt(6)
	v_cvt_pk_bf16_f32 v34, v40, v38
	s_waitcnt lgkmcnt(4)
	v_cvt_pk_bf16_f32 v35, v42, v44
	s_waitcnt lgkmcnt(2)
	v_cvt_pk_bf16_f32 v36, v46, v48
	s_waitcnt lgkmcnt(0)
	v_cvt_pk_bf16_f32 v37, v66, v68
	v_lshl_add_u64 v[72:73], v[70:71], 0, v[72:73]
	v_add_u32_e32 v38, s8, v52
	global_store_dwordx4 v[72:73], v[34:37], off
	s_nop 1
	v_cvt_pk_bf16_f32 v34, v41, v39
	v_ashrrev_i32_e32 v39, 31, v38
	v_cvt_pk_bf16_f32 v35, v43, v45
	v_cvt_pk_bf16_f32 v36, v47, v49
	v_cvt_pk_bf16_f32 v37, v67, v69
	v_lshlrev_b64 v[38:39], 11, v[38:39]
	ds_read2_b32 v[40:41], v51 offset0:49 offset1:57
	ds_read2_b32 v[42:43], v51 offset0:16 offset1:24
	ds_read2_b32 v[44:45], v51 offset0:82 offset1:90
	ds_read2_b32 v[46:47], v51 offset0:115 offset1:123
	ds_read2_b32 v[48:49], v51 offset0:148 offset1:156
	ds_read2_b32 v[66:67], v51 offset0:181 offset1:189
	ds_read2_b32 v[68:69], v51 offset0:214 offset1:222
	ds_read2_b32 v[72:73], v51 offset0:247 offset1:255
	v_lshl_add_u64 v[38:39], v[70:71], 0, v[38:39]
	global_store_dwordx4 v[38:39], v[34:37], off
	v_add_u32_e32 v38, s8, v53
	v_ashrrev_i32_e32 v39, 31, v38
	v_lshlrev_b64 v[38:39], 11, v[38:39]
	s_waitcnt lgkmcnt(6)
	v_cvt_pk_bf16_f32 v34, v42, v40
	s_waitcnt lgkmcnt(4)
	v_cvt_pk_bf16_f32 v35, v44, v46
	s_waitcnt lgkmcnt(2)
	v_cvt_pk_bf16_f32 v36, v48, v66
	s_waitcnt lgkmcnt(0)
	v_cvt_pk_bf16_f32 v37, v68, v72
	v_lshl_add_u64 v[38:39], v[70:71], 0, v[38:39]
	global_store_dwordx4 v[38:39], v[34:37], off
	v_add_u32_e32 v38, s8, v54
	v_ashrrev_i32_e32 v39, 31, v38
	v_lshlrev_b64 v[38:39], 11, v[38:39]
	v_cvt_pk_bf16_f32 v34, v43, v41
	v_cvt_pk_bf16_f32 v35, v45, v47
	v_cvt_pk_bf16_f32 v36, v49, v67
	v_cvt_pk_bf16_f32 v37, v69, v73
	v_lshl_add_u64 v[38:39], v[70:71], 0, v[38:39]
	global_store_dwordx4 v[38:39], v[34:37], off
	s_waitcnt lgkmcnt(0)

; #define LAS __attribute__((address_space(3)))
; template <class KS>
; __device__ __forceinline__ void p0_transpose_item(const float* W, int K, int N, bf16* WT, int kb, int nb, int prow, LAS float* scr, int lane, const KS& ks) {
;     const int k0 = 64 * kb, n0 = 32 * nb;
; #pragma unroll 8
;     for (int i = 0; i < 32; ++i) { const int kk = 2 * i + (lane >> 5); scr[kk * 33 + (lane & 31)] = W[(size_t)(k0 + kk) * N + n0 + (lane & 31)] * ks(k0 + kk); }
; __device__ __forceinline__ void convert_items(KArgs A, unsigned char* ws, LAS unsigned char* lds, int it0, int it1, int gw, int NGW, int wave, int lane) {
;     ...
;         if (r < CI_OUT) { const int kb = r / 32, nb = r % 32; const float* sg = A->in.subg; const float* og = A->in.ong;
;             p0_transpose_item(A->in.wout, DM, DM, WOUT, kb, nb, 32 * nb, scr, lane, [sg, og](int k) { return k < 512 ? 0.8f * sg[k & 127] : og[k & 127]; }); continue; } r -= CI_OUT;
.LBB0_369:
	s_andn2_b64 vcc, exec, s[8:9]
	s_cbranch_vccnz .LBB0_405
	s_and_b32 s8, s18, 0x7f
	s_lshl_b32 s12, s8, 6
	s_lshl_b32 s8, s24, 2
	s_and_b32 s20, s8, 0xf80
	s_load_dwordx2 s[18:19], s[14:15], 0x60
	s_load_dwordx4 s[8:11], s[14:15], 0x70
	v_add_u32_e32 v34, s12, v57
	v_add_u32_e32 v36, s12, v58
	v_add_u32_e32 v38, s12, v59
	v_add_u32_e32 v40, s12, v60
	v_add_u32_e32 v42, s12, v61
	v_add_u32_e32 v44, s12, v62
	v_add_u32_e32 v46, s12, v63
	v_add_u32_e32 v48, s12, v64
	v_ashrrev_i32_e32 v35, 31, v34
	v_ashrrev_i32_e32 v37, 31, v36
	v_ashrrev_i32_e32 v39, 31, v38
	v_ashrrev_i32_e32 v41, 31, v40
	v_ashrrev_i32_e32 v43, 31, v42
	v_ashrrev_i32_e32 v45, 31, v44
	v_ashrrev_i32_e32 v47, 31, v46
	v_ashrrev_i32_e32 v49, 31, v48
	s_waitcnt lgkmcnt(0)
	s_add_u32 s10, s10, s20
	v_lshlrev_b64 v[34:35], 12, v[34:35]
	v_lshlrev_b64 v[36:37], 12, v[36:37]
	v_lshlrev_b64 v[38:39], 12, v[38:39]
	v_lshlrev_b64 v[40:41], 12, v[40:41]
	v_lshlrev_b64 v[42:43], 12, v[42:43]
	v_lshlrev_b64 v[44:45], 12, v[44:45]
	v_lshlrev_b64 v[46:47], 12, v[46:47]
	v_lshlrev_b64 v[48:49], 12, v[48:49]
	s_addc_u32 s11, s11, 0
	v_add_u32_e32 v6, s12, v2
	v_lshl_add_u64 v[34:35], s[10:11], 0, v[34:35]
	v_lshl_add_u64 v[36:37], s[10:11], 0, v[36:37]
	v_lshl_add_u64 v[38:39], s[10:11], 0, v[38:39]
	v_lshl_add_u64 v[40:41], s[10:11], 0, v[40:41]
	v_lshl_add_u64 v[42:43], s[10:11], 0, v[42:43]
	v_lshl_add_u64 v[44:45], s[10:11], 0, v[44:45]
	v_lshl_add_u64 v[46:47], s[10:11], 0, v[46:47]
	v_lshl_add_u64 v[48:49], s[10:11], 0, v[48:49]
	v_add_u32_e32 v145, 0xfffff200, v6
	v_lshl_add_u64 v[142:143], v[48:49], 0, v[8:9]
	global_load_dword v192, v[142:143], off
	v_and_b32_e32 v144, 0x7f, v145
	v_lshlrev_b32_e32 v144, 2, v144
	global_load_dword v200, v144, s[8:9]
	global_load_dword v208, v144, s[18:19]
	v_lshl_add_u64 v[142:143], v[46:47], 0, v[8:9]
	global_load_dword v193, v[142:143], off
	v_add_u32_e32 v144, 2, v145
	v_and_b32_e32 v144, 0x7f, v144
	v_lshlrev_b32_e32 v144, 2, v144
	global_load_dword v201, v144, s[8:9]
	global_load_dword v209, v144, s[18:19]
	v_lshl_add_u64 v[142:143], v[44:45], 0, v[8:9]
	global_load_dword v194, v[142:143], off
	v_add_u32_e32 v144, 4, v145
	v_and_b32_e32 v144, 0x7f, v144
	v_lshlrev_b32_e32 v144, 2, v144
	global_load_dword v202, v144, s[8:9]
	global_load_dword v210, v144, s[18:19]
	v_lshl_add_u64 v[142:143], v[42:43], 0, v[8:9]
	global_load_dword v195, v[142:143], off
	v_add_u32_e32 v144, 6, v145
	v_and_b32_e32 v144, 0x7f, v144
	v_lshlrev_b32_e32 v144, 2, v144
	global_load_dword v203, v144, s[8:9]
	global_load_dword v211, v144, s[18:19]
	v_lshl_add_u64 v[142:143], v[40:41], 0, v[8:9]
	global_load_dword v196, v[142:143], off
	v_add_u32_e32 v144, 8, v145
	v_and_b32_e32 v144, 0x7f, v144
	v_lshlrev_b32_e32 v144, 2, v144
	global_load_dword v204, v144, s[8:9]
	global_load_dword v212, v144, s[18:19]
	v_lshl_add_u64 v[142:143], v[38:39], 0, v[8:9]
	global_load_dword v197, v[142:143], off
	v_add_u32_e32 v144, 10, v145
	v_and_b32_e32 v144, 0x7f, v144
	v_lshlrev_b32_e32 v144, 2, v144
	global_load_dword v205, v144, s[8:9]
	global_load_dword v213, v144, s[18:19]
	v_lshl_add_u64 v[142:143], v[36:37], 0, v[8:9]
	global_load_dword v198, v[142:143], off
	v_add_u32_e32 v144, 12, v145
	v_and_b32_e32 v144, 0x7f, v144
	v_lshlrev_b32_e32 v144, 2, v144
	global_load_dword v206, v144, s[8:9]
	global_load_dword v214, v144, s[18:19]
	v_lshl_add_u64 v[142:143], v[34:35], 0, v[8:9]
	global_load_dword v199, v[142:143], off
	v_add_u32_e32 v144, 14, v145
	v_and_b32_e32 v144, 0x7f, v144
	v_lshlrev_b32_e32 v144, 2, v144
	global_load_dword v207, v144, s[8:9]
	global_load_dword v215, v144, s[18:19]
	v_lshl_add_u64 v[48:49], v[48:49], 0, s[16:17]
	v_lshl_add_u64 v[46:47], v[46:47], 0, s[16:17]
	v_lshl_add_u64 v[44:45], v[44:45], 0, s[16:17]
	v_lshl_add_u64 v[42:43], v[42:43], 0, s[16:17]
	v_lshl_add_u64 v[40:41], v[40:41], 0, s[16:17]
	v_lshl_add_u64 v[38:39], v[38:39], 0, s[16:17]
	v_lshl_add_u64 v[36:37], v[36:37], 0, s[16:17]
	v_lshl_add_u64 v[34:35], v[34:35], 0, s[16:17]
	v_add_u32_e32 v145, 0xfffff210, v6
	v_lshl_add_u64 v[142:143], v[48:49], 0, v[8:9]
	global_load_dword v216, v[142:143], off
	v_and_b32_e32 v144, 0x7f, v145
	v_lshlrev_b32_e32 v144, 2, v144
	global_load_dword v224, v144, s[8:9]
	global_load_dword v134, v144, s[18:19]
	v_lshl_add_u64 v[142:143], v[46:47], 0, v[8:9]
	global_load_dword v217, v[142:143], off
	v_add_u32_e32 v144, 2, v145
	v_and_b32_e32 v144, 0x7f, v144
	v_lshlrev_b32_e32 v144, 2, v144
	global_load_dword v225, v144, s[8:9]
	global_load_dword v135, v144, s[18:19]
	v_lshl_add_u64 v[142:143], v[44:45], 0, v[8:9]
	global_load_dword v218, v[142:143], off
	v_add_u32_e32 v144, 4, v145
	v_and_b32_e32 v144, 0x7f, v144
	v_lshlrev_b32_e32 v144, 2, v144
	global_load_dword v226, v144, s[8:9]
	global_load_dword v136, v144, s[18:19]
	v_lshl_add_u64 v[142:143], v[42:43], 0, v[8:9]
	global_load_dword v219, v[142:143], off
	v_add_u32_e32 v144, 6, v145
	v_and_b32_e32 v144, 0x7f, v144
	v_lshlrev_b32_e32 v144, 2, v144
	global_load_dword v227, v144, s[8:9]
	global_load_dword v137, v144, s[18:19]
	v_lshl_add_u64 v[142:143], v[40:41], 0, v[8:9]
	global_load_dword v220, v[142:143], off
	v_add_u32_e32 v144, 8, v145
	v_and_b32_e32 v144, 0x7f, v144
	v_lshlrev_b32_e32 v144, 2, v144
	global_load_dword v228, v144, s[8:9]
	global_load_dword v138, v144, s[18:19]
	v_lshl_add_u64 v[142:143], v[38:39], 0, v[8:9]
	global_load_dword v221, v[142:143], off
	v_add_u32_e32 v144, 10, v145
	v_and_b32_e32 v144, 0x7f, v144
	v_lshlrev_b32_e32 v144, 2, v144
	global_load_dword v229, v144, s[8:9]
	global_load_dword v139, v144, s[18:19]
	v_lshl_add_u64 v[142:143], v[36:37], 0, v[8:9]
	global_load_dword v222, v[142:143], off
	v_add_u32_e32 v144, 12, v145
	v_and_b32_e32 v144, 0x7f, v144
	v_lshlrev_b32_e32 v144, 2, v144
	global_load_dword v232, v144, s[8:9]
	global_load_dword v140, v144, s[18:19]
	v_lshl_add_u64 v[142:143], v[34:35], 0, v[8:9]
	global_load_dword v223, v[142:143], off
	v_add_u32_e32 v144, 14, v145
	v_and_b32_e32 v144, 0x7f, v144
	v_lshlrev_b32_e32 v144, 2, v144
	global_load_dword v233, v144, s[8:9]
	global_load_dword v141, v144, s[18:19]
	v_lshl_add_u64 v[48:49], v[48:49], 0, s[16:17]
	v_lshl_add_u64 v[46:47], v[46:47], 0, s[16:17]
	v_lshl_add_u64 v[44:45], v[44:45], 0, s[16:17]
	v_lshl_add_u64 v[42:43], v[42:43], 0, s[16:17]
	v_lshl_add_u64 v[40:41], v[40:41], 0, s[16:17]
	v_lshl_add_u64 v[38:39], v[38:39], 0, s[16:17]
	v_lshl_add_u64 v[36:37], v[36:37], 0, s[16:17]
	v_lshl_add_u64 v[34:35], v[34:35], 0, s[16:17]
	s_waitcnt vmcnt(24)
; template <class KS>
; __device__ __forceinline__ void p0_transpose_item(const float* W, int K, int N, bf16* WT, int kb, int nb, int prow, LAS float* scr, int lane, const KS& ks) {
;     ...
; #pragma unroll 8
;     for (int i = 0; i < 32; ++i) { const int kk = 2 * i + (lane >> 5); scr[kk * 33 + (lane & 31)] = W[(size_t)(k0 + kk) * N + n0 + (lane & 31)] * ks(k0 + kk); }
; __device__ __forceinline__ void convert_items(KArgs A, unsigned char* ws, LAS unsigned char* lds, int it0, int it1, int gw, int NGW, int wave, int lane) {
;     ...
;         if (r < CI_OUT) { const int kb = r / 32, nb = r % 32; const float* sg = A->in.subg; const float* og = A->in.ong;
;             p0_transpose_item(A->in.wout, DM, DM, WOUT, kb, nb, 32 * nb, scr, lane, [sg, og](int k) { return k < 512 ? 0.8f * sg[k & 127] : og[k & 127]; }); continue; } r -= CI_OUT;
	v_add_u32_e32 v144, 0xfffff200, v6
	v_cmp_lt_i32_e32 vcc, s29, v144
	v_mul_f32_e32 v208, 0x3f4ccccd, v208
	s_nop 1
	v_cndmask_b32_e32 v144, v208, v200, vcc
	v_mul_f32_e32 v192, v192, v144
	ds_write_b32 v56, v192
	v_add_u32_e32 v144, 0xfffff202, v6
	v_cmp_lt_i32_e32 vcc, s29, v144
	v_mul_f32_e32 v209, 0x3f4ccccd, v209
	s_nop 1
	v_cndmask_b32_e32 v144, v209, v201, vcc
	v_mul_f32_e32 v193, v193, v144
	ds_write_b32 v56, v193 offset:264
	v_add_u32_e32 v144, 0xfffff204, v6
	v_cmp_lt_i32_e32 vcc, s29, v144
	v_mul_f32_e32 v210, 0x3f4ccccd, v210
	s_nop 1
	v_cndmask_b32_e32 v144, v210, v202, vcc
	v_mul_f32_e32 v194, v194, v144
	ds_write_b32 v56, v194 offset:528
	v_add_u32_e32 v144, 0xfffff206, v6
	v_cmp_lt_i32_e32 vcc, s29, v144
	v_mul_f32_e32 v211, 0x3f4ccccd, v211
	s_nop 1
	v_cndmask_b32_e32 v144, v211, v203, vcc
	v_mul_f32_e32 v195, v195, v144
	ds_write_b32 v56, v195 offset:792
	v_add_u32_e32 v144, 0xfffff208, v6
	v_cmp_lt_i32_e32 vcc, s29, v144
	v_mul_f32_e32 v212, 0x3f4ccccd, v212
	s_nop 1
	v_cndmask_b32_e32 v144, v212, v204, vcc
	v_mul_f32_e32 v196, v196, v144
	ds_write_b32 v56, v196 offset:1056
	v_add_u32_e32 v144, 0xfffff20a, v6
	v_cmp_lt_i32_e32 vcc, s29, v144
	v_mul_f32_e32 v213, 0x3f4ccccd, v213
	s_nop 1
	v_cndmask_b32_e32 v144, v213, v205, vcc
	v_mul_f32_e32 v197, v197, v144
	ds_write_b32 v56, v197 offset:1320
	v_add_u32_e32 v144, 0xfffff20c, v6
	v_cmp_lt_i32_e32 vcc, s29, v144
	v_mul_f32_e32 v214, 0x3f4ccccd, v214
	s_nop 1
	v_cndmask_b32_e32 v144, v214, v206, vcc
	v_mul_f32_e32 v198, v198, v144
	ds_write_b32 v56, v198 offset:1584
	v_add_u32_e32 v144, 0xfffff20e, v6
	v_cmp_lt_i32_e32 vcc, s29, v144
	v_mul_f32_e32 v215, 0x3f4ccccd, v215
	s_nop 1
	v_cndmask_b32_e32 v144, v215, v207, vcc
	v_mul_f32_e32 v199, v199, v144
	ds_write_b32 v56, v199 offset:1848
	v_add_u32_e32 v145, 0xfffff220, v6
	v_lshl_add_u64 v[142:143], v[48:49], 0, v[8:9]
	global_load_dword v192, v[142:143], off
	v_and_b32_e32 v144, 0x7f, v145
	v_lshlrev_b32_e32 v144, 2, v144
	global_load_dword v200, v144, s[8:9]
	global_load_dword v208, v144, s[18:19]
	v_lshl_add_u64 v[142:143], v[46:47], 0, v[8:9]
	global_load_dword v193, v[142:143], off
	v_add_u32_e32 v144, 2, v145
	v_and_b32_e32 v144, 0x7f, v144
	v_lshlrev_b32_e32 v144, 2, v144
	global_load_dword v201, v144, s[8:9]
	global_load_dword v209, v144, s[18:19]
	v_lshl_add_u64 v[142:143], v[44:45], 0, v[8:9]
	global_load_dword v194, v[142:143], off
	v_add_u32_e32 v144, 4, v145
	v_and_b32_e32 v144, 0x7f, v144
	v_lshlrev_b32_e32 v144, 2, v144
	global_load_dword v202, v144, s[8:9]
	global_load_dword v210, v144, s[18:19]
	v_lshl_add_u64 v[142:143], v[42:43], 0, v[8:9]
	global_load_dword v195, v[142:143], off
	v_add_u32_e32 v144, 6, v145
	v_and_b32_e32 v144, 0x7f, v144
	v_lshlrev_b32_e32 v144, 2, v144
	global_load_dword v203, v144, s[8:9]
	global_load_dword v211, v144, s[18:19]
	v_lshl_add_u64 v[142:143], v[40:41], 0, v[8:9]
	global_load_dword v196, v[142:143], off
	v_add_u32_e32 v144, 8, v145
	v_and_b32_e32 v144, 0x7f, v144
	v_lshlrev_b32_e32 v144, 2, v144
	global_load_dword v204, v144, s[8:9]
	global_load_dword v212, v144, s[18:19]
	v_lshl_add_u64 v[142:143], v[38:39], 0, v[8:9]
	global_load_dword v197, v[142:143], off
	v_add_u32_e32 v144, 10, v145
	v_and_b32_e32 v144, 0x7f, v144
	v_lshlrev_b32_e32 v144, 2, v144
	global_load_dword v205, v144, s[8:9]
	global_load_dword v213, v144, s[18:19]
	v_lshl_add_u64 v[142:143], v[36:37], 0, v[8:9]
	global_load_dword v198, v[142:143], off
	v_add_u32_e32 v144, 12, v145
	v_and_b32_e32 v144, 0x7f, v144
	v_lshlrev_b32_e32 v144, 2, v144
	global_load_dword v206, v144, s[8:9]
	global_load_dword v214, v144, s[18:19]
	v_lshl_add_u64 v[142:143], v[34:35], 0, v[8:9]
	global_load_dword v199, v[142:143], off
	v_add_u32_e32 v144, 14, v145
	v_and_b32_e32 v144, 0x7f, v144
	v_lshlrev_b32_e32 v144, 2, v144
	global_load_dword v207, v144, s[8:9]
	global_load_dword v215, v144, s[18:19]
	v_lshl_add_u64 v[48:49], v[48:49], 0, s[16:17]
	v_lshl_add_u64 v[46:47], v[46:47], 0, s[16:17]
	v_lshl_add_u64 v[44:45], v[44:45], 0, s[16:17]
	v_lshl_add_u64 v[42:43], v[42:43], 0, s[16:17]
	v_lshl_add_u64 v[40:41], v[40:41], 0, s[16:17]
	v_lshl_add_u64 v[38:39], v[38:39], 0, s[16:17]
	v_lshl_add_u64 v[36:37], v[36:37], 0, s[16:17]
	v_lshl_add_u64 v[34:35], v[34:35], 0, s[16:17]
	s_waitcnt vmcnt(24)
; template <class KS>
; __device__ __forceinline__ void p0_transpose_item(const float* W, int K, int N, bf16* WT, int kb, int nb, int prow, LAS float* scr, int lane, const KS& ks) {
;     ...
; #pragma unroll 8
;     for (int i = 0; i < 32; ++i) { const int kk = 2 * i + (lane >> 5); scr[kk * 33 + (lane & 31)] = W[(size_t)(k0 + kk) * N + n0 + (lane & 31)] * ks(k0 + kk); }
; __device__ __forceinline__ void convert_items(KArgs A, unsigned char* ws, LAS unsigned char* lds, int it0, int it1, int gw, int NGW, int wave, int lane) {
;     ...
;         if (r < CI_OUT) { const int kb = r / 32, nb = r % 32; const float* sg = A->in.subg; const float* og = A->in.ong;
;             p0_transpose_item(A->in.wout, DM, DM, WOUT, kb, nb, 32 * nb, scr, lane, [sg, og](int k) { return k < 512 ? 0.8f * sg[k & 127] : og[k & 127]; }); continue; } r -= CI_OUT;
	v_add_u32_e32 v144, 0xfffff210, v6
	v_cmp_lt_i32_e32 vcc, s29, v144
	v_mul_f32_e32 v134, 0x3f4ccccd, v134
	s_nop 1
	v_cndmask_b32_e32 v144, v134, v224, vcc
	v_mul_f32_e32 v216, v216, v144
	ds_write_b32 v56, v216 offset:2112
	v_add_u32_e32 v144, 0xfffff212, v6
	v_cmp_lt_i32_e32 vcc, s29, v144
	v_mul_f32_e32 v135, 0x3f4ccccd, v135
	s_nop 1
	v_cndmask_b32_e32 v144, v135, v225, vcc
	v_mul_f32_e32 v217, v217, v144
	ds_write_b32 v56, v217 offset:2376
	v_add_u32_e32 v144, 0xfffff214, v6
	v_cmp_lt_i32_e32 vcc, s29, v144
	v_mul_f32_e32 v136, 0x3f4ccccd, v136
	s_nop 1
	v_cndmask_b32_e32 v144, v136, v226, vcc
	v_mul_f32_e32 v218, v218, v144
	ds_write_b32 v56, v218 offset:2640
	v_add_u32_e32 v144, 0xfffff216, v6
	v_cmp_lt_i32_e32 vcc, s29, v144
	v_mul_f32_e32 v137, 0x3f4ccccd, v137
	s_nop 1
	v_cndmask_b32_e32 v144, v137, v227, vcc
	v_mul_f32_e32 v219, v219, v144
	ds_write_b32 v56, v219 offset:2904
	v_add_u32_e32 v144, 0xfffff218, v6
	v_cmp_lt_i32_e32 vcc, s29, v144
	v_mul_f32_e32 v138, 0x3f4ccccd, v138
	s_nop 1
	v_cndmask_b32_e32 v144, v138, v228, vcc
	v_mul_f32_e32 v220, v220, v144
	ds_write_b32 v56, v220 offset:3168
	v_add_u32_e32 v144, 0xfffff21a, v6
	v_cmp_lt_i32_e32 vcc, s29, v144
	v_mul_f32_e32 v139, 0x3f4ccccd, v139
	s_nop 1
	v_cndmask_b32_e32 v144, v139, v229, vcc
	v_mul_f32_e32 v221, v221, v144
	ds_write_b32 v56, v221 offset:3432
	v_add_u32_e32 v144, 0xfffff21c, v6
	v_cmp_lt_i32_e32 vcc, s29, v144
	v_mul_f32_e32 v140, 0x3f4ccccd, v140
	s_nop 1
	v_cndmask_b32_e32 v144, v140, v232, vcc
	v_mul_f32_e32 v222, v222, v144
	ds_write_b32 v56, v222 offset:3696
	v_add_u32_e32 v144, 0xfffff21e, v6
	v_cmp_lt_i32_e32 vcc, s29, v144
	v_mul_f32_e32 v141, 0x3f4ccccd, v141
	s_nop 1
	v_cndmask_b32_e32 v144, v141, v233, vcc
	v_mul_f32_e32 v223, v223, v144
	ds_write_b32 v56, v223 offset:3960
	v_add_u32_e32 v145, 0xfffff230, v6
	v_lshl_add_u64 v[142:143], v[48:49], 0, v[8:9]
	global_load_dword v216, v[142:143], off
	v_and_b32_e32 v144, 0x7f, v145
	v_lshlrev_b32_e32 v144, 2, v144
	global_load_dword v224, v144, s[8:9]
	global_load_dword v134, v144, s[18:19]
	v_lshl_add_u64 v[142:143], v[46:47], 0, v[8:9]
	global_load_dword v217, v[142:143], off
	v_add_u32_e32 v144, 2, v145
	v_and_b32_e32 v144, 0x7f, v144
	v_lshlrev_b32_e32 v144, 2, v144
	global_load_dword v225, v144, s[8:9]
	global_load_dword v135, v144, s[18:19]
	v_lshl_add_u64 v[142:143], v[44:45], 0, v[8:9]
	global_load_dword v218, v[142:143], off
	v_add_u32_e32 v144, 4, v145
	v_and_b32_e32 v144, 0x7f, v144
	v_lshlrev_b32_e32 v144, 2, v144
	global_load_dword v226, v144, s[8:9]
	global_load_dword v136, v144, s[18:19]
	v_lshl_add_u64 v[142:143], v[42:43], 0, v[8:9]
	global_load_dword v219, v[142:143], off
	v_add_u32_e32 v144, 6, v145
	v_and_b32_e32 v144, 0x7f, v144
	v_lshlrev_b32_e32 v144, 2, v144
	global_load_dword v227, v144, s[8:9]
	global_load_dword v137, v144, s[18:19]
	v_lshl_add_u64 v[142:143], v[40:41], 0, v[8:9]
	global_load_dword v220, v[142:143], off
	v_add_u32_e32 v144, 8, v145
	v_and_b32_e32 v144, 0x7f, v144
	v_lshlrev_b32_e32 v144, 2, v144
	global_load_dword v228, v144, s[8:9]
	global_load_dword v138, v144, s[18:19]
	v_lshl_add_u64 v[142:143], v[38:39], 0, v[8:9]
	global_load_dword v221, v[142:143], off
	v_add_u32_e32 v144, 10, v145
	v_and_b32_e32 v144, 0x7f, v144
	v_lshlrev_b32_e32 v144, 2, v144
	global_load_dword v229, v144, s[8:9]
	global_load_dword v139, v144, s[18:19]
	v_lshl_add_u64 v[142:143], v[36:37], 0, v[8:9]
	global_load_dword v222, v[142:143], off
	v_add_u32_e32 v144, 12, v145
	v_and_b32_e32 v144, 0x7f, v144
	v_lshlrev_b32_e32 v144, 2, v144
	global_load_dword v232, v144, s[8:9]
	global_load_dword v140, v144, s[18:19]
	v_lshl_add_u64 v[142:143], v[34:35], 0, v[8:9]
	global_load_dword v223, v[142:143], off
	v_add_u32_e32 v144, 14, v145
	v_and_b32_e32 v144, 0x7f, v144
	v_lshlrev_b32_e32 v144, 2, v144
	global_load_dword v233, v144, s[8:9]
	global_load_dword v141, v144, s[18:19]
	s_waitcnt vmcnt(24)
; template <class KS>
; __device__ __forceinline__ void p0_transpose_item(const float* W, int K, int N, bf16* WT, int kb, int nb, int prow, LAS float* scr, int lane, const KS& ks) {
;     ...
; #pragma unroll 8
;     for (int i = 0; i < 32; ++i) { const int kk = 2 * i + (lane >> 5); scr[kk * 33 + (lane & 31)] = W[(size_t)(k0 + kk) * N + n0 + (lane & 31)] * ks(k0 + kk); }
; __device__ __forceinline__ void convert_items(KArgs A, unsigned char* ws, LAS unsigned char* lds, int it0, int it1, int gw, int NGW, int wave, int lane) {
;     ...
;         if (r < CI_OUT) { const int kb = r / 32, nb = r % 32; const float* sg = A->in.subg; const float* og = A->in.ong;
;             p0_transpose_item(A->in.wout, DM, DM, WOUT, kb, nb, 32 * nb, scr, lane, [sg, og](int k) { return k < 512 ? 0.8f * sg[k & 127] : og[k & 127]; }); continue; } r -= CI_OUT;
	v_add_u32_e32 v144, 0xfffff220, v6
	v_cmp_lt_i32_e32 vcc, s29, v144
	v_mul_f32_e32 v208, 0x3f4ccccd, v208
	s_nop 1
	v_cndmask_b32_e32 v144, v208, v200, vcc
	v_mul_f32_e32 v192, v192, v144
	ds_write_b32 v56, v192 offset:4224
	v_add_u32_e32 v144, 0xfffff222, v6
	v_cmp_lt_i32_e32 vcc, s29, v144
	v_mul_f32_e32 v209, 0x3f4ccccd, v209
	s_nop 1
	v_cndmask_b32_e32 v144, v209, v201, vcc
	v_mul_f32_e32 v193, v193, v144
	ds_write_b32 v56, v193 offset:4488
	v_add_u32_e32 v144, 0xfffff224, v6
	v_cmp_lt_i32_e32 vcc, s29, v144
	v_mul_f32_e32 v210, 0x3f4ccccd, v210
	s_nop 1
	v_cndmask_b32_e32 v144, v210, v202, vcc
	v_mul_f32_e32 v194, v194, v144
	ds_write_b32 v56, v194 offset:4752
	v_add_u32_e32 v144, 0xfffff226, v6
	v_cmp_lt_i32_e32 vcc, s29, v144
	v_mul_f32_e32 v211, 0x3f4ccccd, v211
	s_nop 1
	v_cndmask_b32_e32 v144, v211, v203, vcc
	v_mul_f32_e32 v195, v195, v144
	ds_write_b32 v56, v195 offset:5016
	v_add_u32_e32 v144, 0xfffff228, v6
	v_cmp_lt_i32_e32 vcc, s29, v144
	v_mul_f32_e32 v212, 0x3f4ccccd, v212
	s_nop 1
	v_cndmask_b32_e32 v144, v212, v204, vcc
	v_mul_f32_e32 v196, v196, v144
	ds_write_b32 v56, v196 offset:5280
	v_add_u32_e32 v144, 0xfffff22a, v6
	v_cmp_lt_i32_e32 vcc, s29, v144
	v_mul_f32_e32 v213, 0x3f4ccccd, v213
	s_nop 1
	v_cndmask_b32_e32 v144, v213, v205, vcc
	v_mul_f32_e32 v197, v197, v144
	ds_write_b32 v56, v197 offset:5544
	v_add_u32_e32 v144, 0xfffff22c, v6
	v_cmp_lt_i32_e32 vcc, s29, v144
	v_mul_f32_e32 v214, 0x3f4ccccd, v214
	s_nop 1
	v_cndmask_b32_e32 v144, v214, v206, vcc
	v_mul_f32_e32 v198, v198, v144
	ds_write_b32 v56, v198 offset:5808
	v_add_u32_e32 v144, 0xfffff22e, v6
	v_cmp_lt_i32_e32 vcc, s29, v144
	v_mul_f32_e32 v215, 0x3f4ccccd, v215
	s_nop 1
	v_cndmask_b32_e32 v144, v215, v207, vcc
	v_mul_f32_e32 v199, v199, v144
	ds_write_b32 v56, v199 offset:6072
	s_waitcnt vmcnt(0)
	v_add_u32_e32 v144, 0xfffff230, v6
	v_cmp_lt_i32_e32 vcc, s29, v144
	v_mul_f32_e32 v134, 0x3f4ccccd, v134
	s_nop 1
	v_cndmask_b32_e32 v144, v134, v224, vcc
	v_mul_f32_e32 v216, v216, v144
	ds_write_b32 v56, v216 offset:6336
	v_add_u32_e32 v144, 0xfffff232, v6
	v_cmp_lt_i32_e32 vcc, s29, v144
	v_mul_f32_e32 v135, 0x3f4ccccd, v135
	s_nop 1
	v_cndmask_b32_e32 v144, v135, v225, vcc
	v_mul_f32_e32 v217, v217, v144
	ds_write_b32 v56, v217 offset:6600
	v_add_u32_e32 v144, 0xfffff234, v6
	v_cmp_lt_i32_e32 vcc, s29, v144
	v_mul_f32_e32 v136, 0x3f4ccccd, v136
	s_nop 1
	v_cndmask_b32_e32 v144, v136, v226, vcc
	v_mul_f32_e32 v218, v218, v144
	ds_write_b32 v56, v218 offset:6864
	v_add_u32_e32 v144, 0xfffff236, v6
	v_cmp_lt_i32_e32 vcc, s29, v144
	v_mul_f32_e32 v137, 0x3f4ccccd, v137
	s_nop 1
	v_cndmask_b32_e32 v144, v137, v227, vcc
	v_mul_f32_e32 v219, v219, v144
	ds_write_b32 v56, v219 offset:7128
	v_add_u32_e32 v144, 0xfffff238, v6
	v_cmp_lt_i32_e32 vcc, s29, v144
	v_mul_f32_e32 v138, 0x3f4ccccd, v138
	s_nop 1
	v_cndmask_b32_e32 v144, v138, v228, vcc
	v_mul_f32_e32 v220, v220, v144
	ds_write_b32 v56, v220 offset:7392
	v_add_u32_e32 v144, 0xfffff23a, v6
	v_cmp_lt_i32_e32 vcc, s29, v144
	v_mul_f32_e32 v139, 0x3f4ccccd, v139
	s_nop 1
	v_cndmask_b32_e32 v144, v139, v229, vcc
	v_mul_f32_e32 v221, v221, v144
	ds_write_b32 v56, v221 offset:7656
	v_add_u32_e32 v144, 0xfffff23c, v6
	v_cmp_lt_i32_e32 vcc, s29, v144
	v_mul_f32_e32 v140, 0x3f4ccccd, v140
	s_nop 1
	v_cndmask_b32_e32 v144, v140, v232, vcc
	v_mul_f32_e32 v222, v222, v144
	ds_write_b32 v56, v222 offset:7920
	v_add_u32_e32 v144, 0xfffff23e, v6
	v_cmp_lt_i32_e32 vcc, s29, v144
	v_mul_f32_e32 v141, 0x3f4ccccd, v141
	s_nop 1
	v_cndmask_b32_e32 v144, v141, v233, vcc
	v_mul_f32_e32 v223, v223, v144
	ds_write_b32 v56, v223 offset:8184
